# P5 gate-up epilogue row blocks rewritten: conv taps via v_fmac_f32_dpp row_shr/row_shl carries, packed f32 scale/sigmoid tail, full exec + masked store
# speedup vs baseline: 1.0049x; 1.0049x over previous
.LBB0_642:
	s_mul_i32 s53, s12, 0xfe
	v_add_u32_e32 v181, s53, v184
	v_med3_i32 v52, v181, 0, v192
	v_add_u32_e32 v204, 16, v181
	v_add_u32_e32 v202, 32, v181
	v_add_u32_e32 v200, 48, v181
	v_add_u32_e32 v198, 64, v181
	v_add_u32_e32 v196, 0x50, v181
	v_add_u32_e32 v194, 0x60, v181
	v_add_u32_e32 v193, 0x70, v181
	s_lshl_b32 s3, s10, 7
	v_lshlrev_b32_e32 v52, 2, v52
	v_med3_i32 v53, v204, 0, v192
	v_med3_i32 v54, v202, 0, v192
	v_med3_i32 v55, v200, 0, v192
	v_med3_i32 v56, v198, 0, v192
	v_med3_i32 v57, v196, 0, v192
	v_med3_i32 v58, v194, 0, v192
	v_med3_i32 v59, v193, 0, v192
	s_or_b32 s12, s3, s74
	v_lshlrev_b32_e32 v53, 2, v53
	v_lshlrev_b32_e32 v54, 2, v54
	v_lshlrev_b32_e32 v55, 2, v55
	v_lshlrev_b32_e32 v56, 2, v56
	v_lshlrev_b32_e32 v57, 2, v57
	v_lshlrev_b32_e32 v58, 2, v58
	v_lshlrev_b32_e32 v59, 2, v59
	global_load_dword v168, v52, s[28:29]
	global_load_dword v206, v53, s[28:29]
	global_load_dword v205, v54, s[28:29]
	global_load_dword v203, v55, s[28:29]
	global_load_dword v201, v56, s[28:29]
	global_load_dword v199, v57, s[28:29]
	global_load_dword v197, v58, s[28:29]
	global_load_dword v180, v59, s[28:29]
	v_or_b32_e32 v52, s12, v170
	v_ashrrev_i32_e32 v53, 31, v52
	v_lshlrev_b64 v[52:53], 2, v[52:53]
	v_mov_b32_e32 v229, v52
	v_lshl_add_u64 v[54:55], s[50:51], 0, v[52:53]
	v_lshl_add_u64 v[60:61], s[46:47], 0, v[52:53]
	v_lshl_add_u64 v[64:65], s[48:49], 0, v[52:53]
	v_lshl_add_u64 v[52:53], s[20:21], 0, v[52:53]
	global_load_dwordx4 v[76:79], v[54:55], off offset:16
	global_load_dwordx4 v[56:59], v[54:55], off
	global_load_dwordx4 v[80:83], v[60:61], off offset:16
	s_nop 0
	global_load_dwordx4 v[60:63], v[60:61], off
	s_nop 0
	global_load_dwordx4 v[84:87], v[64:65], off offset:16
	s_nop 0
	global_load_dwordx4 v[64:67], v[64:65], off
	s_nop 0
	global_load_dwordx4 v[72:75], v[52:53], off offset:16
	s_nop 0
	global_load_dwordx4 v[52:55], v[52:53], off
	s_waitcnt vmcnt(0)
	v_fmamk_f32 v180, v180, 0x39800000, v191
	v_rsq_f32_e32 v180, v180
	s_and_saveexec_b64 s[10:11], s[44:45]
	s_cbranch_execz .LBB0_644
	v_pk_mul_f32 v[208:209], v[12:13], v[180:181] op_sel_hi:[1,0]
	v_pk_mul_f32 v[210:211], v[14:15], v[180:181] op_sel_hi:[1,0]
	ds_write_b128 v186, v[208:211]
	v_pk_mul_f32 v[208:209], v[8:9], v[180:181] op_sel_hi:[1,0]
	v_pk_mul_f32 v[210:211], v[10:11], v[180:181] op_sel_hi:[1,0]
	ds_write_b128 v187, v[208:211]

.LBB0_661:
	s_waitcnt lgkmcnt(0)
	s_ashr_i32 s60, s12, 5
	s_ashr_i32 s61, s60, 31
	v_mbcnt_lo_u32_b32 v225, -1, 0
	v_mbcnt_hi_u32_b32 v225, -1, v225
	v_and_b32_e32 v225, 15, v225
	v_cmp_eq_u32_e64 s[98:99], 14, v225
	s_mov_b32 s100, 0xbfb8aa3b
	s_mov_b32 s101, 0xbfb8aa3b
	s_nop 1
	v_cndmask_b32_e64 v209, v209, v212, s[98:99]
	v_cndmask_b32_e64 v215, v215, v216, s[98:99]
	v_cndmask_b32_e64 v219, v219, v222, s[98:99]
	v_cndmask_b32_e64 v223, v223, v224, s[98:99]
	v_cndmask_b32_e64 v228, v228, v230, s[98:99]
	v_cndmask_b32_e64 v232, v232, v233, s[98:99]
	v_cndmask_b32_e64 v236, v236, v183, s[98:99]
	v_cndmask_b32_e64 v237, v237, v238, s[98:99]
	v_lshlrev_b32_e32 v252, 5, v181
	v_and_b32_e32 v252, 0x1e0, v252
	v_lshlrev_b32_e32 v252, 1, v252
	v_lshl_add_u32 v252, v170, 1, v252
	v_mov_b32_e32 v253, 0
	v_ashrrev_i32_e32 v225, 4, v181
	v_mov_b64_e32 v[234:235], s[60:61]
	v_mad_i64_i32 v[234:235], s[98:99], v225, s82, v[234:235]
	v_lshlrev_b64 v[234:235], 10, v[234:235]
	v_lshl_add_u64 v[234:235], s[36:37], 0, v[234:235]
	v_lshl_add_u64 v[234:235], v[234:235], 0, v[252:253]
	v_mov_b32_e32 v238, 0x56000
	v_mov_b32_e32 v239, 0
	v_fmamk_f32 v230, v168, 0x39800000, v191
	v_rsq_f32_e32 v230, v230
	v_and_b32_e32 v224, 0xfff, v181
	v_cmp_le_i32_e64 s[12:13], s53, v181
	v_cmp_gt_i32_e64 s[14:15], s73, v181
	v_cmp_gt_u32_e32 vcc, 2, v224
	v_pk_mul_f32 v[156:157], v[156:157], v[230:231] op_sel_hi:[1,0]
	v_pk_mul_f32 v[158:159], v[158:159], v[230:231] op_sel_hi:[1,0]
	v_pk_mul_f32 v[152:153], v[152:153], v[230:231] op_sel_hi:[1,0]
	v_pk_mul_f32 v[154:155], v[154:155], v[230:231] op_sel_hi:[1,0]
	v_pk_mul_f32 v[144:145], v[144:145], v[230:231] op_sel_hi:[1,0]
	v_pk_mul_f32 v[146:147], v[146:147], v[230:231] op_sel_hi:[1,0]
	v_pk_mul_f32 v[148:149], v[148:149], v[230:231] op_sel_hi:[1,0]
	v_pk_mul_f32 v[150:151], v[150:151], v[230:231] op_sel_hi:[1,0]
	s_cmp_eq_u64 vcc, 0
	s_cbranch_scc1 .Lgu_nss0
	v_cmp_eq_u32_e64 s[98:99], 0, v224
	s_nop 1
	v_cndmask_b32_e64 v56, v56, 0, vcc
	v_cndmask_b32_e64 v57, v57, 0, vcc
	v_cndmask_b32_e64 v58, v58, 0, vcc
	v_cndmask_b32_e64 v59, v59, 0, vcc
	v_cndmask_b32_e64 v76, v76, 0, vcc
	v_cndmask_b32_e64 v77, v77, 0, vcc
	v_cndmask_b32_e64 v78, v78, 0, vcc
	v_cndmask_b32_e64 v79, v79, 0, vcc
	v_cndmask_b32_e64 v60, v60, 0, s[98:99]
	v_cndmask_b32_e64 v61, v61, 0, s[98:99]
	v_cndmask_b32_e64 v62, v62, 0, s[98:99]
	v_cndmask_b32_e64 v63, v63, 0, s[98:99]
	v_cndmask_b32_e64 v80, v80, 0, s[98:99]
	v_cndmask_b32_e64 v81, v81, 0, s[98:99]
	v_cndmask_b32_e64 v82, v82, 0, s[98:99]
	v_cndmask_b32_e64 v83, v83, 0, s[98:99]
.Lgu_nss0:
	v_mov_b32_e32 v244, v52
	v_mov_b32_e32 v245, v53
	v_mov_b32_e32 v246, v54
	v_mov_b32_e32 v247, v55
	v_mov_b32_e32 v248, v72
	v_mov_b32_e32 v249, v73
	v_mov_b32_e32 v250, v74
	v_mov_b32_e32 v251, v75
	v_fmac_f32_dpp v244, v156, v56 row_shr:2 row_mask:0xf bank_mask:0xf bound_ctrl:0
	v_fmac_f32_dpp v245, v157, v57 row_shr:2 row_mask:0xf bank_mask:0xf bound_ctrl:0
	v_fmac_f32_dpp v246, v158, v58 row_shr:2 row_mask:0xf bank_mask:0xf bound_ctrl:0
	v_fmac_f32_dpp v247, v159, v59 row_shr:2 row_mask:0xf bank_mask:0xf bound_ctrl:0
	v_fmac_f32_dpp v248, v152, v76 row_shr:2 row_mask:0xf bank_mask:0xf bound_ctrl:0
	v_fmac_f32_dpp v249, v153, v77 row_shr:2 row_mask:0xf bank_mask:0xf bound_ctrl:0
	v_fmac_f32_dpp v250, v154, v78 row_shr:2 row_mask:0xf bank_mask:0xf bound_ctrl:0
	v_fmac_f32_dpp v251, v155, v79 row_shr:2 row_mask:0xf bank_mask:0xf bound_ctrl:0
	v_fmac_f32_dpp v244, v209, v56 row_shl:14 row_mask:0xf bank_mask:0xf bound_ctrl:0
	v_fmac_f32_dpp v245, v215, v57 row_shl:14 row_mask:0xf bank_mask:0xf bound_ctrl:0
	v_fmac_f32_dpp v246, v219, v58 row_shl:14 row_mask:0xf bank_mask:0xf bound_ctrl:0
	v_fmac_f32_dpp v247, v223, v59 row_shl:14 row_mask:0xf bank_mask:0xf bound_ctrl:0
	v_fmac_f32_dpp v248, v228, v76 row_shl:14 row_mask:0xf bank_mask:0xf bound_ctrl:0
	v_fmac_f32_dpp v249, v232, v77 row_shl:14 row_mask:0xf bank_mask:0xf bound_ctrl:0
	v_fmac_f32_dpp v250, v236, v78 row_shl:14 row_mask:0xf bank_mask:0xf bound_ctrl:0
	v_fmac_f32_dpp v251, v237, v79 row_shl:14 row_mask:0xf bank_mask:0xf bound_ctrl:0
	v_fmac_f32_dpp v244, v156, v60 row_shr:1 row_mask:0xf bank_mask:0xf bound_ctrl:0
	v_fmac_f32_dpp v245, v157, v61 row_shr:1 row_mask:0xf bank_mask:0xf bound_ctrl:0
	v_fmac_f32_dpp v246, v158, v62 row_shr:1 row_mask:0xf bank_mask:0xf bound_ctrl:0
	v_fmac_f32_dpp v247, v159, v63 row_shr:1 row_mask:0xf bank_mask:0xf bound_ctrl:0
	v_fmac_f32_dpp v248, v152, v80 row_shr:1 row_mask:0xf bank_mask:0xf bound_ctrl:0
	v_fmac_f32_dpp v249, v153, v81 row_shr:1 row_mask:0xf bank_mask:0xf bound_ctrl:0
	v_fmac_f32_dpp v250, v154, v82 row_shr:1 row_mask:0xf bank_mask:0xf bound_ctrl:0
	v_fmac_f32_dpp v251, v155, v83 row_shr:1 row_mask:0xf bank_mask:0xf bound_ctrl:0
	v_fmac_f32_dpp v244, v209, v60 row_shl:15 row_mask:0xf bank_mask:0xf bound_ctrl:0
	v_fmac_f32_dpp v245, v215, v61 row_shl:15 row_mask:0xf bank_mask:0xf bound_ctrl:0
	v_fmac_f32_dpp v246, v219, v62 row_shl:15 row_mask:0xf bank_mask:0xf bound_ctrl:0
	v_fmac_f32_dpp v247, v223, v63 row_shl:15 row_mask:0xf bank_mask:0xf bound_ctrl:0
	v_fmac_f32_dpp v248, v228, v80 row_shl:15 row_mask:0xf bank_mask:0xf bound_ctrl:0
	v_fmac_f32_dpp v249, v232, v81 row_shl:15 row_mask:0xf bank_mask:0xf bound_ctrl:0
	v_fmac_f32_dpp v250, v236, v82 row_shl:15 row_mask:0xf bank_mask:0xf bound_ctrl:0
	v_fmac_f32_dpp v251, v237, v83 row_shl:15 row_mask:0xf bank_mask:0xf bound_ctrl:0
	v_fmac_f32_e32 v244, v64, v156
	v_fmac_f32_e32 v245, v65, v157
	v_fmac_f32_e32 v246, v66, v158
	v_fmac_f32_e32 v247, v67, v159
	v_fmac_f32_e32 v248, v84, v152
	v_fmac_f32_e32 v249, v85, v153
	v_fmac_f32_e32 v250, v86, v154
	v_fmac_f32_e32 v251, v87, v155
	v_pk_mul_f32 v[210:211], v[244:245], s[100:101]
	v_pk_mul_f32 v[212:213], v[246:247], s[100:101]
	v_pk_mul_f32 v[216:217], v[248:249], s[100:101]
	v_pk_mul_f32 v[220:221], v[250:251], s[100:101]
	v_exp_f32_e32 v210, v210
	v_exp_f32_e32 v211, v211
	v_exp_f32_e32 v212, v212
	v_exp_f32_e32 v213, v213
	v_exp_f32_e32 v216, v216
	v_exp_f32_e32 v217, v217
	v_exp_f32_e32 v220, v220
	v_exp_f32_e32 v221, v221
	v_pk_add_f32 v[210:211], v[210:211], 1.0 op_sel_hi:[1,0]
	v_pk_add_f32 v[212:213], v[212:213], 1.0 op_sel_hi:[1,0]
	v_pk_add_f32 v[216:217], v[216:217], 1.0 op_sel_hi:[1,0]
	v_pk_add_f32 v[220:221], v[220:221], 1.0 op_sel_hi:[1,0]
	v_rcp_f32_e32 v210, v210
	v_rcp_f32_e32 v211, v211
	v_rcp_f32_e32 v212, v212
	v_rcp_f32_e32 v213, v213
	v_rcp_f32_e32 v216, v216
	v_rcp_f32_e32 v217, v217
	v_rcp_f32_e32 v220, v220
	v_rcp_f32_e32 v221, v221
	v_pk_mul_f32 v[244:245], v[244:245], v[210:211]
	v_pk_mul_f32 v[246:247], v[246:247], v[212:213]
	v_pk_mul_f32 v[248:249], v[248:249], v[216:217]
	v_pk_mul_f32 v[250:251], v[250:251], v[220:221]
	v_pk_mul_f32 v[244:245], v[144:145], v[244:245]
	v_pk_mul_f32 v[246:247], v[146:147], v[246:247]
	v_pk_mul_f32 v[248:249], v[148:149], v[248:249]
	v_pk_mul_f32 v[250:251], v[150:151], v[250:251]
	v_cvt_pk_bf16_f32 v240, v244, v245
	v_cvt_pk_bf16_f32 v241, v246, v247
	v_cvt_pk_bf16_f32 v242, v248, v249
	v_cvt_pk_bf16_f32 v243, v250, v251
	s_and_b64 s[12:13], s[12:13], s[14:15]
	s_and_saveexec_b64 s[62:63], s[12:13]
	global_store_dwordx4 v[234:235], v[240:243], off
	s_or_b64 exec, exec, s[62:63]
	s_cmp_eq_u64 vcc, 0
	s_cbranch_scc1 .Lgu_nrl0
	global_load_dwordx4 v[76:79], v229, s[50:51] offset:16
	global_load_dwordx4 v[56:59], v229, s[50:51]
	global_load_dwordx4 v[80:83], v229, s[46:47] offset:16
	global_load_dwordx4 v[60:63], v229, s[46:47]
	s_waitcnt vmcnt(0)
.Lgu_nrl0:
	v_fmamk_f32 v230, v206, 0x39800000, v191
	v_rsq_f32_e32 v230, v230
	v_and_b32_e32 v224, 0xfff, v204
	v_cmp_le_i32_e64 s[12:13], s53, v204
	v_cmp_gt_i32_e64 s[14:15], s83, v181
	v_cmp_gt_u32_e32 vcc, 2, v224
	v_pk_mul_f32 v[140:141], v[140:141], v[230:231] op_sel_hi:[1,0]
	v_pk_mul_f32 v[142:143], v[142:143], v[230:231] op_sel_hi:[1,0]
	v_pk_mul_f32 v[136:137], v[136:137], v[230:231] op_sel_hi:[1,0]
	v_pk_mul_f32 v[138:139], v[138:139], v[230:231] op_sel_hi:[1,0]
	v_pk_mul_f32 v[128:129], v[128:129], v[230:231] op_sel_hi:[1,0]
	v_pk_mul_f32 v[130:131], v[130:131], v[230:231] op_sel_hi:[1,0]
	v_pk_mul_f32 v[132:133], v[132:133], v[230:231] op_sel_hi:[1,0]
	v_pk_mul_f32 v[134:135], v[134:135], v[230:231] op_sel_hi:[1,0]
	s_cmp_eq_u64 vcc, 0
	s_cbranch_scc1 .Lgu_nss1
	v_cmp_eq_u32_e64 s[98:99], 0, v224
	s_nop 1
	v_cndmask_b32_e64 v56, v56, 0, vcc
	v_cndmask_b32_e64 v57, v57, 0, vcc
	v_cndmask_b32_e64 v58, v58, 0, vcc
	v_cndmask_b32_e64 v59, v59, 0, vcc
	v_cndmask_b32_e64 v76, v76, 0, vcc
	v_cndmask_b32_e64 v77, v77, 0, vcc
	v_cndmask_b32_e64 v78, v78, 0, vcc
	v_cndmask_b32_e64 v79, v79, 0, vcc
	v_cndmask_b32_e64 v60, v60, 0, s[98:99]
	v_cndmask_b32_e64 v61, v61, 0, s[98:99]
	v_cndmask_b32_e64 v62, v62, 0, s[98:99]
	v_cndmask_b32_e64 v63, v63, 0, s[98:99]
	v_cndmask_b32_e64 v80, v80, 0, s[98:99]
	v_cndmask_b32_e64 v81, v81, 0, s[98:99]
	v_cndmask_b32_e64 v82, v82, 0, s[98:99]
	v_cndmask_b32_e64 v83, v83, 0, s[98:99]
.Lgu_nss1:
	v_mov_b32_e32 v244, v52
	v_mov_b32_e32 v245, v53
	v_mov_b32_e32 v246, v54
	v_mov_b32_e32 v247, v55
	v_mov_b32_e32 v248, v72
	v_mov_b32_e32 v249, v73
	v_mov_b32_e32 v250, v74
	v_mov_b32_e32 v251, v75
	v_fmac_f32_dpp v244, v140, v56 row_shr:2 row_mask:0xf bank_mask:0xf bound_ctrl:0
	v_fmac_f32_dpp v245, v141, v57 row_shr:2 row_mask:0xf bank_mask:0xf bound_ctrl:0
	v_fmac_f32_dpp v246, v142, v58 row_shr:2 row_mask:0xf bank_mask:0xf bound_ctrl:0
	v_fmac_f32_dpp v247, v143, v59 row_shr:2 row_mask:0xf bank_mask:0xf bound_ctrl:0
	v_fmac_f32_dpp v248, v136, v76 row_shr:2 row_mask:0xf bank_mask:0xf bound_ctrl:0
	v_fmac_f32_dpp v249, v137, v77 row_shr:2 row_mask:0xf bank_mask:0xf bound_ctrl:0
	v_fmac_f32_dpp v250, v138, v78 row_shr:2 row_mask:0xf bank_mask:0xf bound_ctrl:0
	v_fmac_f32_dpp v251, v139, v79 row_shr:2 row_mask:0xf bank_mask:0xf bound_ctrl:0
	v_fmac_f32_dpp v244, v156, v56 row_shl:14 row_mask:0xf bank_mask:0xf bound_ctrl:0
	v_fmac_f32_dpp v245, v157, v57 row_shl:14 row_mask:0xf bank_mask:0xf bound_ctrl:0
	v_fmac_f32_dpp v246, v158, v58 row_shl:14 row_mask:0xf bank_mask:0xf bound_ctrl:0
	v_fmac_f32_dpp v247, v159, v59 row_shl:14 row_mask:0xf bank_mask:0xf bound_ctrl:0
	v_fmac_f32_dpp v248, v152, v76 row_shl:14 row_mask:0xf bank_mask:0xf bound_ctrl:0
	v_fmac_f32_dpp v249, v153, v77 row_shl:14 row_mask:0xf bank_mask:0xf bound_ctrl:0
	v_fmac_f32_dpp v250, v154, v78 row_shl:14 row_mask:0xf bank_mask:0xf bound_ctrl:0
	v_fmac_f32_dpp v251, v155, v79 row_shl:14 row_mask:0xf bank_mask:0xf bound_ctrl:0
	v_fmac_f32_dpp v244, v140, v60 row_shr:1 row_mask:0xf bank_mask:0xf bound_ctrl:0
	v_fmac_f32_dpp v245, v141, v61 row_shr:1 row_mask:0xf bank_mask:0xf bound_ctrl:0
	v_fmac_f32_dpp v246, v142, v62 row_shr:1 row_mask:0xf bank_mask:0xf bound_ctrl:0
	v_fmac_f32_dpp v247, v143, v63 row_shr:1 row_mask:0xf bank_mask:0xf bound_ctrl:0
	v_fmac_f32_dpp v248, v136, v80 row_shr:1 row_mask:0xf bank_mask:0xf bound_ctrl:0
	v_fmac_f32_dpp v249, v137, v81 row_shr:1 row_mask:0xf bank_mask:0xf bound_ctrl:0
	v_fmac_f32_dpp v250, v138, v82 row_shr:1 row_mask:0xf bank_mask:0xf bound_ctrl:0
	v_fmac_f32_dpp v251, v139, v83 row_shr:1 row_mask:0xf bank_mask:0xf bound_ctrl:0
	v_fmac_f32_dpp v244, v156, v60 row_shl:15 row_mask:0xf bank_mask:0xf bound_ctrl:0
	v_fmac_f32_dpp v245, v157, v61 row_shl:15 row_mask:0xf bank_mask:0xf bound_ctrl:0
	v_fmac_f32_dpp v246, v158, v62 row_shl:15 row_mask:0xf bank_mask:0xf bound_ctrl:0
	v_fmac_f32_dpp v247, v159, v63 row_shl:15 row_mask:0xf bank_mask:0xf bound_ctrl:0
	v_fmac_f32_dpp v248, v152, v80 row_shl:15 row_mask:0xf bank_mask:0xf bound_ctrl:0
	v_fmac_f32_dpp v249, v153, v81 row_shl:15 row_mask:0xf bank_mask:0xf bound_ctrl:0
	v_fmac_f32_dpp v250, v154, v82 row_shl:15 row_mask:0xf bank_mask:0xf bound_ctrl:0
	v_fmac_f32_dpp v251, v155, v83 row_shl:15 row_mask:0xf bank_mask:0xf bound_ctrl:0
	v_fmac_f32_e32 v244, v64, v140
	v_fmac_f32_e32 v245, v65, v141
	v_fmac_f32_e32 v246, v66, v142
	v_fmac_f32_e32 v247, v67, v143
	v_fmac_f32_e32 v248, v84, v136
	v_fmac_f32_e32 v249, v85, v137
	v_fmac_f32_e32 v250, v86, v138
	v_fmac_f32_e32 v251, v87, v139
	v_pk_mul_f32 v[210:211], v[244:245], s[100:101]
	v_pk_mul_f32 v[212:213], v[246:247], s[100:101]
	v_pk_mul_f32 v[216:217], v[248:249], s[100:101]
	v_pk_mul_f32 v[220:221], v[250:251], s[100:101]
	v_exp_f32_e32 v210, v210
	v_exp_f32_e32 v211, v211
	v_exp_f32_e32 v212, v212
	v_exp_f32_e32 v213, v213
	v_exp_f32_e32 v216, v216
	v_exp_f32_e32 v217, v217
	v_exp_f32_e32 v220, v220
	v_exp_f32_e32 v221, v221
	v_pk_add_f32 v[210:211], v[210:211], 1.0 op_sel_hi:[1,0]
	v_pk_add_f32 v[212:213], v[212:213], 1.0 op_sel_hi:[1,0]
	v_pk_add_f32 v[216:217], v[216:217], 1.0 op_sel_hi:[1,0]
	v_pk_add_f32 v[220:221], v[220:221], 1.0 op_sel_hi:[1,0]
	v_rcp_f32_e32 v210, v210
	v_rcp_f32_e32 v211, v211
	v_rcp_f32_e32 v212, v212
	v_rcp_f32_e32 v213, v213
	v_rcp_f32_e32 v216, v216
	v_rcp_f32_e32 v217, v217
	v_rcp_f32_e32 v220, v220
	v_rcp_f32_e32 v221, v221
	v_pk_mul_f32 v[244:245], v[244:245], v[210:211]
	v_pk_mul_f32 v[246:247], v[246:247], v[212:213]
	v_pk_mul_f32 v[248:249], v[248:249], v[216:217]
	v_pk_mul_f32 v[250:251], v[250:251], v[220:221]
	v_pk_mul_f32 v[244:245], v[128:129], v[244:245]
	v_pk_mul_f32 v[246:247], v[130:131], v[246:247]
	v_pk_mul_f32 v[248:249], v[132:133], v[248:249]
	v_pk_mul_f32 v[250:251], v[134:135], v[250:251]
	v_cvt_pk_bf16_f32 v240, v244, v245
	v_cvt_pk_bf16_f32 v241, v246, v247
	v_cvt_pk_bf16_f32 v242, v248, v249
	v_cvt_pk_bf16_f32 v243, v250, v251
	v_lshl_add_u64 v[234:235], v[234:235], 0, v[238:239]
	s_and_b64 s[12:13], s[12:13], s[14:15]
	s_and_saveexec_b64 s[62:63], s[12:13]
	global_store_dwordx4 v[234:235], v[240:243], off
	s_or_b64 exec, exec, s[62:63]
	s_cmp_eq_u64 vcc, 0
	s_cbranch_scc1 .Lgu_nrl1
	global_load_dwordx4 v[76:79], v229, s[50:51] offset:16
	global_load_dwordx4 v[56:59], v229, s[50:51]
	global_load_dwordx4 v[80:83], v229, s[46:47] offset:16
	global_load_dwordx4 v[60:63], v229, s[46:47]
	s_waitcnt vmcnt(0)
.Lgu_nrl1:
	v_fmamk_f32 v230, v205, 0x39800000, v191
	v_rsq_f32_e32 v230, v230
	v_and_b32_e32 v224, 0xfff, v202
	v_cmp_le_i32_e64 s[12:13], s53, v202
	v_cmp_gt_i32_e64 s[14:15], s84, v181
	v_cmp_gt_u32_e32 vcc, 2, v224
	v_pk_mul_f32 v[124:125], v[124:125], v[230:231] op_sel_hi:[1,0]
	v_pk_mul_f32 v[126:127], v[126:127], v[230:231] op_sel_hi:[1,0]
	v_pk_mul_f32 v[120:121], v[120:121], v[230:231] op_sel_hi:[1,0]
	v_pk_mul_f32 v[122:123], v[122:123], v[230:231] op_sel_hi:[1,0]
	v_pk_mul_f32 v[112:113], v[112:113], v[230:231] op_sel_hi:[1,0]
	v_pk_mul_f32 v[114:115], v[114:115], v[230:231] op_sel_hi:[1,0]
	v_pk_mul_f32 v[116:117], v[116:117], v[230:231] op_sel_hi:[1,0]
	v_pk_mul_f32 v[118:119], v[118:119], v[230:231] op_sel_hi:[1,0]
	s_cmp_eq_u64 vcc, 0
	s_cbranch_scc1 .Lgu_nss2
	v_cmp_eq_u32_e64 s[98:99], 0, v224
	s_nop 1
	v_cndmask_b32_e64 v56, v56, 0, vcc
	v_cndmask_b32_e64 v57, v57, 0, vcc
	v_cndmask_b32_e64 v58, v58, 0, vcc
	v_cndmask_b32_e64 v59, v59, 0, vcc
	v_cndmask_b32_e64 v76, v76, 0, vcc
	v_cndmask_b32_e64 v77, v77, 0, vcc
	v_cndmask_b32_e64 v78, v78, 0, vcc
	v_cndmask_b32_e64 v79, v79, 0, vcc
	v_cndmask_b32_e64 v60, v60, 0, s[98:99]
	v_cndmask_b32_e64 v61, v61, 0, s[98:99]
	v_cndmask_b32_e64 v62, v62, 0, s[98:99]
	v_cndmask_b32_e64 v63, v63, 0, s[98:99]
	v_cndmask_b32_e64 v80, v80, 0, s[98:99]
	v_cndmask_b32_e64 v81, v81, 0, s[98:99]
	v_cndmask_b32_e64 v82, v82, 0, s[98:99]
	v_cndmask_b32_e64 v83, v83, 0, s[98:99]
.Lgu_nss2:
	v_mov_b32_e32 v244, v52
	v_mov_b32_e32 v245, v53
	v_mov_b32_e32 v246, v54
	v_mov_b32_e32 v247, v55
	v_mov_b32_e32 v248, v72
	v_mov_b32_e32 v249, v73
	v_mov_b32_e32 v250, v74
	v_mov_b32_e32 v251, v75
	v_fmac_f32_dpp v244, v124, v56 row_shr:2 row_mask:0xf bank_mask:0xf bound_ctrl:0
	v_fmac_f32_dpp v245, v125, v57 row_shr:2 row_mask:0xf bank_mask:0xf bound_ctrl:0
	v_fmac_f32_dpp v246, v126, v58 row_shr:2 row_mask:0xf bank_mask:0xf bound_ctrl:0
	v_fmac_f32_dpp v247, v127, v59 row_shr:2 row_mask:0xf bank_mask:0xf bound_ctrl:0
	v_fmac_f32_dpp v248, v120, v76 row_shr:2 row_mask:0xf bank_mask:0xf bound_ctrl:0
	v_fmac_f32_dpp v249, v121, v77 row_shr:2 row_mask:0xf bank_mask:0xf bound_ctrl:0
	v_fmac_f32_dpp v250, v122, v78 row_shr:2 row_mask:0xf bank_mask:0xf bound_ctrl:0
	v_fmac_f32_dpp v251, v123, v79 row_shr:2 row_mask:0xf bank_mask:0xf bound_ctrl:0
	v_fmac_f32_dpp v244, v140, v56 row_shl:14 row_mask:0xf bank_mask:0xf bound_ctrl:0
	v_fmac_f32_dpp v245, v141, v57 row_shl:14 row_mask:0xf bank_mask:0xf bound_ctrl:0
	v_fmac_f32_dpp v246, v142, v58 row_shl:14 row_mask:0xf bank_mask:0xf bound_ctrl:0
	v_fmac_f32_dpp v247, v143, v59 row_shl:14 row_mask:0xf bank_mask:0xf bound_ctrl:0
	v_fmac_f32_dpp v248, v136, v76 row_shl:14 row_mask:0xf bank_mask:0xf bound_ctrl:0
	v_fmac_f32_dpp v249, v137, v77 row_shl:14 row_mask:0xf bank_mask:0xf bound_ctrl:0
	v_fmac_f32_dpp v250, v138, v78 row_shl:14 row_mask:0xf bank_mask:0xf bound_ctrl:0
	v_fmac_f32_dpp v251, v139, v79 row_shl:14 row_mask:0xf bank_mask:0xf bound_ctrl:0
	v_fmac_f32_dpp v244, v124, v60 row_shr:1 row_mask:0xf bank_mask:0xf bound_ctrl:0
	v_fmac_f32_dpp v245, v125, v61 row_shr:1 row_mask:0xf bank_mask:0xf bound_ctrl:0
	v_fmac_f32_dpp v246, v126, v62 row_shr:1 row_mask:0xf bank_mask:0xf bound_ctrl:0
	v_fmac_f32_dpp v247, v127, v63 row_shr:1 row_mask:0xf bank_mask:0xf bound_ctrl:0
	v_fmac_f32_dpp v248, v120, v80 row_shr:1 row_mask:0xf bank_mask:0xf bound_ctrl:0
	v_fmac_f32_dpp v249, v121, v81 row_shr:1 row_mask:0xf bank_mask:0xf bound_ctrl:0
	v_fmac_f32_dpp v250, v122, v82 row_shr:1 row_mask:0xf bank_mask:0xf bound_ctrl:0
	v_fmac_f32_dpp v251, v123, v83 row_shr:1 row_mask:0xf bank_mask:0xf bound_ctrl:0
	v_fmac_f32_dpp v244, v140, v60 row_shl:15 row_mask:0xf bank_mask:0xf bound_ctrl:0
	v_fmac_f32_dpp v245, v141, v61 row_shl:15 row_mask:0xf bank_mask:0xf bound_ctrl:0
	v_fmac_f32_dpp v246, v142, v62 row_shl:15 row_mask:0xf bank_mask:0xf bound_ctrl:0
	v_fmac_f32_dpp v247, v143, v63 row_shl:15 row_mask:0xf bank_mask:0xf bound_ctrl:0
	v_fmac_f32_dpp v248, v136, v80 row_shl:15 row_mask:0xf bank_mask:0xf bound_ctrl:0
	v_fmac_f32_dpp v249, v137, v81 row_shl:15 row_mask:0xf bank_mask:0xf bound_ctrl:0
	v_fmac_f32_dpp v250, v138, v82 row_shl:15 row_mask:0xf bank_mask:0xf bound_ctrl:0
	v_fmac_f32_dpp v251, v139, v83 row_shl:15 row_mask:0xf bank_mask:0xf bound_ctrl:0
	v_fmac_f32_e32 v244, v64, v124
	v_fmac_f32_e32 v245, v65, v125
	v_fmac_f32_e32 v246, v66, v126
	v_fmac_f32_e32 v247, v67, v127
	v_fmac_f32_e32 v248, v84, v120
	v_fmac_f32_e32 v249, v85, v121
	v_fmac_f32_e32 v250, v86, v122
	v_fmac_f32_e32 v251, v87, v123
	v_pk_mul_f32 v[210:211], v[244:245], s[100:101]
	v_pk_mul_f32 v[212:213], v[246:247], s[100:101]
	v_pk_mul_f32 v[216:217], v[248:249], s[100:101]
	v_pk_mul_f32 v[220:221], v[250:251], s[100:101]
	v_exp_f32_e32 v210, v210
	v_exp_f32_e32 v211, v211
	v_exp_f32_e32 v212, v212
	v_exp_f32_e32 v213, v213
	v_exp_f32_e32 v216, v216
	v_exp_f32_e32 v217, v217
	v_exp_f32_e32 v220, v220
	v_exp_f32_e32 v221, v221
	v_pk_add_f32 v[210:211], v[210:211], 1.0 op_sel_hi:[1,0]
	v_pk_add_f32 v[212:213], v[212:213], 1.0 op_sel_hi:[1,0]
	v_pk_add_f32 v[216:217], v[216:217], 1.0 op_sel_hi:[1,0]
	v_pk_add_f32 v[220:221], v[220:221], 1.0 op_sel_hi:[1,0]
	v_rcp_f32_e32 v210, v210
	v_rcp_f32_e32 v211, v211
	v_rcp_f32_e32 v212, v212
	v_rcp_f32_e32 v213, v213
	v_rcp_f32_e32 v216, v216
	v_rcp_f32_e32 v217, v217
	v_rcp_f32_e32 v220, v220
	v_rcp_f32_e32 v221, v221
	v_pk_mul_f32 v[244:245], v[244:245], v[210:211]
	v_pk_mul_f32 v[246:247], v[246:247], v[212:213]
	v_pk_mul_f32 v[248:249], v[248:249], v[216:217]
	v_pk_mul_f32 v[250:251], v[250:251], v[220:221]
	v_pk_mul_f32 v[244:245], v[112:113], v[244:245]
	v_pk_mul_f32 v[246:247], v[114:115], v[246:247]
	v_pk_mul_f32 v[248:249], v[116:117], v[248:249]
	v_pk_mul_f32 v[250:251], v[118:119], v[250:251]
	v_cvt_pk_bf16_f32 v240, v244, v245
	v_cvt_pk_bf16_f32 v241, v246, v247
	v_cvt_pk_bf16_f32 v242, v248, v249
	v_cvt_pk_bf16_f32 v243, v250, v251
	v_lshl_add_u64 v[234:235], v[234:235], 0, v[238:239]
	s_and_b64 s[12:13], s[12:13], s[14:15]
	s_and_saveexec_b64 s[62:63], s[12:13]
	global_store_dwordx4 v[234:235], v[240:243], off
	s_or_b64 exec, exec, s[62:63]
	s_cmp_eq_u64 vcc, 0
	s_cbranch_scc1 .Lgu_nrl2
	global_load_dwordx4 v[76:79], v229, s[50:51] offset:16
	global_load_dwordx4 v[56:59], v229, s[50:51]
	global_load_dwordx4 v[80:83], v229, s[46:47] offset:16
	global_load_dwordx4 v[60:63], v229, s[46:47]
	s_waitcnt vmcnt(0)
.Lgu_nrl2:
	v_fmamk_f32 v230, v203, 0x39800000, v191
	v_rsq_f32_e32 v230, v230
	v_and_b32_e32 v224, 0xfff, v200
	v_cmp_le_i32_e64 s[12:13], s53, v200
	v_cmp_gt_i32_e64 s[14:15], s85, v181
	v_cmp_gt_u32_e32 vcc, 2, v224
	v_pk_mul_f32 v[108:109], v[108:109], v[230:231] op_sel_hi:[1,0]
	v_pk_mul_f32 v[110:111], v[110:111], v[230:231] op_sel_hi:[1,0]
	v_pk_mul_f32 v[104:105], v[104:105], v[230:231] op_sel_hi:[1,0]
	v_pk_mul_f32 v[106:107], v[106:107], v[230:231] op_sel_hi:[1,0]
	v_pk_mul_f32 v[96:97], v[96:97], v[230:231] op_sel_hi:[1,0]
	v_pk_mul_f32 v[98:99], v[98:99], v[230:231] op_sel_hi:[1,0]
	v_pk_mul_f32 v[100:101], v[100:101], v[230:231] op_sel_hi:[1,0]
	v_pk_mul_f32 v[102:103], v[102:103], v[230:231] op_sel_hi:[1,0]
	s_cmp_eq_u64 vcc, 0
	s_cbranch_scc1 .Lgu_nss3
	v_cmp_eq_u32_e64 s[98:99], 0, v224
	s_nop 1
	v_cndmask_b32_e64 v56, v56, 0, vcc
	v_cndmask_b32_e64 v57, v57, 0, vcc
	v_cndmask_b32_e64 v58, v58, 0, vcc
	v_cndmask_b32_e64 v59, v59, 0, vcc
	v_cndmask_b32_e64 v76, v76, 0, vcc
	v_cndmask_b32_e64 v77, v77, 0, vcc
	v_cndmask_b32_e64 v78, v78, 0, vcc
	v_cndmask_b32_e64 v79, v79, 0, vcc
	v_cndmask_b32_e64 v60, v60, 0, s[98:99]
	v_cndmask_b32_e64 v61, v61, 0, s[98:99]
	v_cndmask_b32_e64 v62, v62, 0, s[98:99]
	v_cndmask_b32_e64 v63, v63, 0, s[98:99]
	v_cndmask_b32_e64 v80, v80, 0, s[98:99]
	v_cndmask_b32_e64 v81, v81, 0, s[98:99]
	v_cndmask_b32_e64 v82, v82, 0, s[98:99]
	v_cndmask_b32_e64 v83, v83, 0, s[98:99]
.Lgu_nss3:
	v_mov_b32_e32 v244, v52
	v_mov_b32_e32 v245, v53
	v_mov_b32_e32 v246, v54
	v_mov_b32_e32 v247, v55
	v_mov_b32_e32 v248, v72
	v_mov_b32_e32 v249, v73
	v_mov_b32_e32 v250, v74
	v_mov_b32_e32 v251, v75
	v_fmac_f32_dpp v244, v108, v56 row_shr:2 row_mask:0xf bank_mask:0xf bound_ctrl:0
	v_fmac_f32_dpp v245, v109, v57 row_shr:2 row_mask:0xf bank_mask:0xf bound_ctrl:0
	v_fmac_f32_dpp v246, v110, v58 row_shr:2 row_mask:0xf bank_mask:0xf bound_ctrl:0
	v_fmac_f32_dpp v247, v111, v59 row_shr:2 row_mask:0xf bank_mask:0xf bound_ctrl:0
	v_fmac_f32_dpp v248, v104, v76 row_shr:2 row_mask:0xf bank_mask:0xf bound_ctrl:0
	v_fmac_f32_dpp v249, v105, v77 row_shr:2 row_mask:0xf bank_mask:0xf bound_ctrl:0
	v_fmac_f32_dpp v250, v106, v78 row_shr:2 row_mask:0xf bank_mask:0xf bound_ctrl:0
	v_fmac_f32_dpp v251, v107, v79 row_shr:2 row_mask:0xf bank_mask:0xf bound_ctrl:0
	v_fmac_f32_dpp v244, v124, v56 row_shl:14 row_mask:0xf bank_mask:0xf bound_ctrl:0
	v_fmac_f32_dpp v245, v125, v57 row_shl:14 row_mask:0xf bank_mask:0xf bound_ctrl:0
	v_fmac_f32_dpp v246, v126, v58 row_shl:14 row_mask:0xf bank_mask:0xf bound_ctrl:0
	v_fmac_f32_dpp v247, v127, v59 row_shl:14 row_mask:0xf bank_mask:0xf bound_ctrl:0
	v_fmac_f32_dpp v248, v120, v76 row_shl:14 row_mask:0xf bank_mask:0xf bound_ctrl:0
	v_fmac_f32_dpp v249, v121, v77 row_shl:14 row_mask:0xf bank_mask:0xf bound_ctrl:0
	v_fmac_f32_dpp v250, v122, v78 row_shl:14 row_mask:0xf bank_mask:0xf bound_ctrl:0
	v_fmac_f32_dpp v251, v123, v79 row_shl:14 row_mask:0xf bank_mask:0xf bound_ctrl:0
	v_fmac_f32_dpp v244, v108, v60 row_shr:1 row_mask:0xf bank_mask:0xf bound_ctrl:0
	v_fmac_f32_dpp v245, v109, v61 row_shr:1 row_mask:0xf bank_mask:0xf bound_ctrl:0
	v_fmac_f32_dpp v246, v110, v62 row_shr:1 row_mask:0xf bank_mask:0xf bound_ctrl:0
	v_fmac_f32_dpp v247, v111, v63 row_shr:1 row_mask:0xf bank_mask:0xf bound_ctrl:0
	v_fmac_f32_dpp v248, v104, v80 row_shr:1 row_mask:0xf bank_mask:0xf bound_ctrl:0
	v_fmac_f32_dpp v249, v105, v81 row_shr:1 row_mask:0xf bank_mask:0xf bound_ctrl:0
	v_fmac_f32_dpp v250, v106, v82 row_shr:1 row_mask:0xf bank_mask:0xf bound_ctrl:0
	v_fmac_f32_dpp v251, v107, v83 row_shr:1 row_mask:0xf bank_mask:0xf bound_ctrl:0
	v_fmac_f32_dpp v244, v124, v60 row_shl:15 row_mask:0xf bank_mask:0xf bound_ctrl:0
	v_fmac_f32_dpp v245, v125, v61 row_shl:15 row_mask:0xf bank_mask:0xf bound_ctrl:0
	v_fmac_f32_dpp v246, v126, v62 row_shl:15 row_mask:0xf bank_mask:0xf bound_ctrl:0
	v_fmac_f32_dpp v247, v127, v63 row_shl:15 row_mask:0xf bank_mask:0xf bound_ctrl:0
	v_fmac_f32_dpp v248, v120, v80 row_shl:15 row_mask:0xf bank_mask:0xf bound_ctrl:0
	v_fmac_f32_dpp v249, v121, v81 row_shl:15 row_mask:0xf bank_mask:0xf bound_ctrl:0
	v_fmac_f32_dpp v250, v122, v82 row_shl:15 row_mask:0xf bank_mask:0xf bound_ctrl:0
	v_fmac_f32_dpp v251, v123, v83 row_shl:15 row_mask:0xf bank_mask:0xf bound_ctrl:0
	v_fmac_f32_e32 v244, v64, v108
	v_fmac_f32_e32 v245, v65, v109
	v_fmac_f32_e32 v246, v66, v110
	v_fmac_f32_e32 v247, v67, v111
	v_fmac_f32_e32 v248, v84, v104
	v_fmac_f32_e32 v249, v85, v105
	v_fmac_f32_e32 v250, v86, v106
	v_fmac_f32_e32 v251, v87, v107
	v_pk_mul_f32 v[210:211], v[244:245], s[100:101]
	v_pk_mul_f32 v[212:213], v[246:247], s[100:101]
	v_pk_mul_f32 v[216:217], v[248:249], s[100:101]
	v_pk_mul_f32 v[220:221], v[250:251], s[100:101]
	v_exp_f32_e32 v210, v210
	v_exp_f32_e32 v211, v211
	v_exp_f32_e32 v212, v212
	v_exp_f32_e32 v213, v213
	v_exp_f32_e32 v216, v216
	v_exp_f32_e32 v217, v217
	v_exp_f32_e32 v220, v220
	v_exp_f32_e32 v221, v221
	v_pk_add_f32 v[210:211], v[210:211], 1.0 op_sel_hi:[1,0]
	v_pk_add_f32 v[212:213], v[212:213], 1.0 op_sel_hi:[1,0]
	v_pk_add_f32 v[216:217], v[216:217], 1.0 op_sel_hi:[1,0]
	v_pk_add_f32 v[220:221], v[220:221], 1.0 op_sel_hi:[1,0]
	v_rcp_f32_e32 v210, v210
	v_rcp_f32_e32 v211, v211
	v_rcp_f32_e32 v212, v212
	v_rcp_f32_e32 v213, v213
	v_rcp_f32_e32 v216, v216
	v_rcp_f32_e32 v217, v217
	v_rcp_f32_e32 v220, v220
	v_rcp_f32_e32 v221, v221
	v_pk_mul_f32 v[244:245], v[244:245], v[210:211]
	v_pk_mul_f32 v[246:247], v[246:247], v[212:213]
	v_pk_mul_f32 v[248:249], v[248:249], v[216:217]
	v_pk_mul_f32 v[250:251], v[250:251], v[220:221]
	v_pk_mul_f32 v[244:245], v[96:97], v[244:245]
	v_pk_mul_f32 v[246:247], v[98:99], v[246:247]
	v_pk_mul_f32 v[248:249], v[100:101], v[248:249]
	v_pk_mul_f32 v[250:251], v[102:103], v[250:251]
	v_cvt_pk_bf16_f32 v240, v244, v245
	v_cvt_pk_bf16_f32 v241, v246, v247
	v_cvt_pk_bf16_f32 v242, v248, v249
	v_cvt_pk_bf16_f32 v243, v250, v251
	v_lshl_add_u64 v[234:235], v[234:235], 0, v[238:239]
	s_and_b64 s[12:13], s[12:13], s[14:15]
	s_and_saveexec_b64 s[62:63], s[12:13]
	global_store_dwordx4 v[234:235], v[240:243], off
	s_or_b64 exec, exec, s[62:63]
	s_cmp_eq_u64 vcc, 0
	s_cbranch_scc1 .Lgu_nrl3
	global_load_dwordx4 v[76:79], v229, s[50:51] offset:16
	global_load_dwordx4 v[56:59], v229, s[50:51]
	global_load_dwordx4 v[80:83], v229, s[46:47] offset:16
	global_load_dwordx4 v[60:63], v229, s[46:47]
	s_waitcnt vmcnt(0)
.Lgu_nrl3:
	v_fmamk_f32 v230, v201, 0x39800000, v191
	v_rsq_f32_e32 v230, v230
	v_and_b32_e32 v224, 0xfff, v198
	v_cmp_le_i32_e64 s[12:13], s53, v198
	v_cmp_gt_i32_e64 s[14:15], s86, v181
	v_cmp_gt_u32_e32 vcc, 2, v224
	v_pk_mul_f32 v[92:93], v[92:93], v[230:231] op_sel_hi:[1,0]
	v_pk_mul_f32 v[94:95], v[94:95], v[230:231] op_sel_hi:[1,0]
	v_pk_mul_f32 v[88:89], v[88:89], v[230:231] op_sel_hi:[1,0]
	v_pk_mul_f32 v[90:91], v[90:91], v[230:231] op_sel_hi:[1,0]
	v_pk_mul_f32 v[48:49], v[48:49], v[230:231] op_sel_hi:[1,0]
	v_pk_mul_f32 v[50:51], v[50:51], v[230:231] op_sel_hi:[1,0]
	v_pk_mul_f32 v[68:69], v[68:69], v[230:231] op_sel_hi:[1,0]
	v_pk_mul_f32 v[70:71], v[70:71], v[230:231] op_sel_hi:[1,0]
	s_cmp_eq_u64 vcc, 0
	s_cbranch_scc1 .Lgu_nss4
	v_cmp_eq_u32_e64 s[98:99], 0, v224
	s_nop 1
	v_cndmask_b32_e64 v56, v56, 0, vcc
	v_cndmask_b32_e64 v57, v57, 0, vcc
	v_cndmask_b32_e64 v58, v58, 0, vcc
	v_cndmask_b32_e64 v59, v59, 0, vcc
	v_cndmask_b32_e64 v76, v76, 0, vcc
	v_cndmask_b32_e64 v77, v77, 0, vcc
	v_cndmask_b32_e64 v78, v78, 0, vcc
	v_cndmask_b32_e64 v79, v79, 0, vcc
	v_cndmask_b32_e64 v60, v60, 0, s[98:99]
	v_cndmask_b32_e64 v61, v61, 0, s[98:99]
	v_cndmask_b32_e64 v62, v62, 0, s[98:99]
	v_cndmask_b32_e64 v63, v63, 0, s[98:99]
	v_cndmask_b32_e64 v80, v80, 0, s[98:99]
	v_cndmask_b32_e64 v81, v81, 0, s[98:99]
	v_cndmask_b32_e64 v82, v82, 0, s[98:99]
	v_cndmask_b32_e64 v83, v83, 0, s[98:99]
.Lgu_nss4:
	v_mov_b32_e32 v244, v52
	v_mov_b32_e32 v245, v53
	v_mov_b32_e32 v246, v54
	v_mov_b32_e32 v247, v55
	v_mov_b32_e32 v248, v72
	v_mov_b32_e32 v249, v73
	v_mov_b32_e32 v250, v74
	v_mov_b32_e32 v251, v75
	v_fmac_f32_dpp v244, v92, v56 row_shr:2 row_mask:0xf bank_mask:0xf bound_ctrl:0
	v_fmac_f32_dpp v245, v93, v57 row_shr:2 row_mask:0xf bank_mask:0xf bound_ctrl:0
	v_fmac_f32_dpp v246, v94, v58 row_shr:2 row_mask:0xf bank_mask:0xf bound_ctrl:0
	v_fmac_f32_dpp v247, v95, v59 row_shr:2 row_mask:0xf bank_mask:0xf bound_ctrl:0
	v_fmac_f32_dpp v248, v88, v76 row_shr:2 row_mask:0xf bank_mask:0xf bound_ctrl:0
	v_fmac_f32_dpp v249, v89, v77 row_shr:2 row_mask:0xf bank_mask:0xf bound_ctrl:0
	v_fmac_f32_dpp v250, v90, v78 row_shr:2 row_mask:0xf bank_mask:0xf bound_ctrl:0
	v_fmac_f32_dpp v251, v91, v79 row_shr:2 row_mask:0xf bank_mask:0xf bound_ctrl:0
	v_fmac_f32_dpp v244, v108, v56 row_shl:14 row_mask:0xf bank_mask:0xf bound_ctrl:0
	v_fmac_f32_dpp v245, v109, v57 row_shl:14 row_mask:0xf bank_mask:0xf bound_ctrl:0
	v_fmac_f32_dpp v246, v110, v58 row_shl:14 row_mask:0xf bank_mask:0xf bound_ctrl:0
	v_fmac_f32_dpp v247, v111, v59 row_shl:14 row_mask:0xf bank_mask:0xf bound_ctrl:0
	v_fmac_f32_dpp v248, v104, v76 row_shl:14 row_mask:0xf bank_mask:0xf bound_ctrl:0
	v_fmac_f32_dpp v249, v105, v77 row_shl:14 row_mask:0xf bank_mask:0xf bound_ctrl:0
	v_fmac_f32_dpp v250, v106, v78 row_shl:14 row_mask:0xf bank_mask:0xf bound_ctrl:0
	v_fmac_f32_dpp v251, v107, v79 row_shl:14 row_mask:0xf bank_mask:0xf bound_ctrl:0
	v_fmac_f32_dpp v244, v92, v60 row_shr:1 row_mask:0xf bank_mask:0xf bound_ctrl:0
	v_fmac_f32_dpp v245, v93, v61 row_shr:1 row_mask:0xf bank_mask:0xf bound_ctrl:0
	v_fmac_f32_dpp v246, v94, v62 row_shr:1 row_mask:0xf bank_mask:0xf bound_ctrl:0
	v_fmac_f32_dpp v247, v95, v63 row_shr:1 row_mask:0xf bank_mask:0xf bound_ctrl:0
	v_fmac_f32_dpp v248, v88, v80 row_shr:1 row_mask:0xf bank_mask:0xf bound_ctrl:0
	v_fmac_f32_dpp v249, v89, v81 row_shr:1 row_mask:0xf bank_mask:0xf bound_ctrl:0
	v_fmac_f32_dpp v250, v90, v82 row_shr:1 row_mask:0xf bank_mask:0xf bound_ctrl:0
	v_fmac_f32_dpp v251, v91, v83 row_shr:1 row_mask:0xf bank_mask:0xf bound_ctrl:0
	v_fmac_f32_dpp v244, v108, v60 row_shl:15 row_mask:0xf bank_mask:0xf bound_ctrl:0
	v_fmac_f32_dpp v245, v109, v61 row_shl:15 row_mask:0xf bank_mask:0xf bound_ctrl:0
	v_fmac_f32_dpp v246, v110, v62 row_shl:15 row_mask:0xf bank_mask:0xf bound_ctrl:0
	v_fmac_f32_dpp v247, v111, v63 row_shl:15 row_mask:0xf bank_mask:0xf bound_ctrl:0
	v_fmac_f32_dpp v248, v104, v80 row_shl:15 row_mask:0xf bank_mask:0xf bound_ctrl:0
	v_fmac_f32_dpp v249, v105, v81 row_shl:15 row_mask:0xf bank_mask:0xf bound_ctrl:0
	v_fmac_f32_dpp v250, v106, v82 row_shl:15 row_mask:0xf bank_mask:0xf bound_ctrl:0
	v_fmac_f32_dpp v251, v107, v83 row_shl:15 row_mask:0xf bank_mask:0xf bound_ctrl:0
	v_fmac_f32_e32 v244, v64, v92
	v_fmac_f32_e32 v245, v65, v93
	v_fmac_f32_e32 v246, v66, v94
	v_fmac_f32_e32 v247, v67, v95
	v_fmac_f32_e32 v248, v84, v88
	v_fmac_f32_e32 v249, v85, v89
	v_fmac_f32_e32 v250, v86, v90
	v_fmac_f32_e32 v251, v87, v91
	v_pk_mul_f32 v[210:211], v[244:245], s[100:101]
	v_pk_mul_f32 v[212:213], v[246:247], s[100:101]
	v_pk_mul_f32 v[216:217], v[248:249], s[100:101]
	v_pk_mul_f32 v[220:221], v[250:251], s[100:101]
	v_exp_f32_e32 v210, v210
	v_exp_f32_e32 v211, v211
	v_exp_f32_e32 v212, v212
	v_exp_f32_e32 v213, v213
	v_exp_f32_e32 v216, v216
	v_exp_f32_e32 v217, v217
	v_exp_f32_e32 v220, v220
	v_exp_f32_e32 v221, v221
	v_pk_add_f32 v[210:211], v[210:211], 1.0 op_sel_hi:[1,0]
	v_pk_add_f32 v[212:213], v[212:213], 1.0 op_sel_hi:[1,0]
	v_pk_add_f32 v[216:217], v[216:217], 1.0 op_sel_hi:[1,0]
	v_pk_add_f32 v[220:221], v[220:221], 1.0 op_sel_hi:[1,0]
	v_rcp_f32_e32 v210, v210
	v_rcp_f32_e32 v211, v211
	v_rcp_f32_e32 v212, v212
	v_rcp_f32_e32 v213, v213
	v_rcp_f32_e32 v216, v216
	v_rcp_f32_e32 v217, v217
	v_rcp_f32_e32 v220, v220
	v_rcp_f32_e32 v221, v221
	v_pk_mul_f32 v[244:245], v[244:245], v[210:211]
	v_pk_mul_f32 v[246:247], v[246:247], v[212:213]
	v_pk_mul_f32 v[248:249], v[248:249], v[216:217]
	v_pk_mul_f32 v[250:251], v[250:251], v[220:221]
	v_pk_mul_f32 v[244:245], v[48:49], v[244:245]
	v_pk_mul_f32 v[246:247], v[50:51], v[246:247]
	v_pk_mul_f32 v[248:249], v[68:69], v[248:249]
	v_pk_mul_f32 v[250:251], v[70:71], v[250:251]
	v_cvt_pk_bf16_f32 v240, v244, v245
	v_cvt_pk_bf16_f32 v241, v246, v247
	v_cvt_pk_bf16_f32 v242, v248, v249
	v_cvt_pk_bf16_f32 v243, v250, v251
	v_lshl_add_u64 v[234:235], v[234:235], 0, v[238:239]
	s_and_b64 s[12:13], s[12:13], s[14:15]
	s_and_saveexec_b64 s[62:63], s[12:13]
	global_store_dwordx4 v[234:235], v[240:243], off
	s_or_b64 exec, exec, s[62:63]
	s_cmp_eq_u64 vcc, 0
	s_cbranch_scc1 .Lgu_nrl4
	global_load_dwordx4 v[76:79], v229, s[50:51] offset:16
	global_load_dwordx4 v[56:59], v229, s[50:51]
	global_load_dwordx4 v[80:83], v229, s[46:47] offset:16
	global_load_dwordx4 v[60:63], v229, s[46:47]
	s_waitcnt vmcnt(0)
.Lgu_nrl4:
	v_fmamk_f32 v230, v199, 0x39800000, v191
	v_rsq_f32_e32 v230, v230
	v_and_b32_e32 v224, 0xfff, v196
	v_cmp_le_i32_e64 s[12:13], s53, v196
	v_cmp_gt_i32_e64 s[14:15], s87, v181
	v_cmp_gt_u32_e32 vcc, 2, v224
	v_pk_mul_f32 v[44:45], v[44:45], v[230:231] op_sel_hi:[1,0]
	v_pk_mul_f32 v[46:47], v[46:47], v[230:231] op_sel_hi:[1,0]
	v_pk_mul_f32 v[40:41], v[40:41], v[230:231] op_sel_hi:[1,0]
	v_pk_mul_f32 v[42:43], v[42:43], v[230:231] op_sel_hi:[1,0]
	v_pk_mul_f32 v[32:33], v[32:33], v[230:231] op_sel_hi:[1,0]
	v_pk_mul_f32 v[34:35], v[34:35], v[230:231] op_sel_hi:[1,0]
	v_pk_mul_f32 v[36:37], v[36:37], v[230:231] op_sel_hi:[1,0]
	v_pk_mul_f32 v[38:39], v[38:39], v[230:231] op_sel_hi:[1,0]
	s_cmp_eq_u64 vcc, 0
	s_cbranch_scc1 .Lgu_nss5
	v_cmp_eq_u32_e64 s[98:99], 0, v224
	s_nop 1
	v_cndmask_b32_e64 v56, v56, 0, vcc
	v_cndmask_b32_e64 v57, v57, 0, vcc
	v_cndmask_b32_e64 v58, v58, 0, vcc
	v_cndmask_b32_e64 v59, v59, 0, vcc
	v_cndmask_b32_e64 v76, v76, 0, vcc
	v_cndmask_b32_e64 v77, v77, 0, vcc
	v_cndmask_b32_e64 v78, v78, 0, vcc
	v_cndmask_b32_e64 v79, v79, 0, vcc
	v_cndmask_b32_e64 v60, v60, 0, s[98:99]
	v_cndmask_b32_e64 v61, v61, 0, s[98:99]
	v_cndmask_b32_e64 v62, v62, 0, s[98:99]
	v_cndmask_b32_e64 v63, v63, 0, s[98:99]
	v_cndmask_b32_e64 v80, v80, 0, s[98:99]
	v_cndmask_b32_e64 v81, v81, 0, s[98:99]
	v_cndmask_b32_e64 v82, v82, 0, s[98:99]
	v_cndmask_b32_e64 v83, v83, 0, s[98:99]
.Lgu_nss5:
	v_mov_b32_e32 v244, v52
	v_mov_b32_e32 v245, v53
	v_mov_b32_e32 v246, v54
	v_mov_b32_e32 v247, v55
	v_mov_b32_e32 v248, v72
	v_mov_b32_e32 v249, v73
	v_mov_b32_e32 v250, v74
	v_mov_b32_e32 v251, v75
	v_fmac_f32_dpp v244, v44, v56 row_shr:2 row_mask:0xf bank_mask:0xf bound_ctrl:0
	v_fmac_f32_dpp v245, v45, v57 row_shr:2 row_mask:0xf bank_mask:0xf bound_ctrl:0
	v_fmac_f32_dpp v246, v46, v58 row_shr:2 row_mask:0xf bank_mask:0xf bound_ctrl:0
	v_fmac_f32_dpp v247, v47, v59 row_shr:2 row_mask:0xf bank_mask:0xf bound_ctrl:0
	v_fmac_f32_dpp v248, v40, v76 row_shr:2 row_mask:0xf bank_mask:0xf bound_ctrl:0
	v_fmac_f32_dpp v249, v41, v77 row_shr:2 row_mask:0xf bank_mask:0xf bound_ctrl:0
	v_fmac_f32_dpp v250, v42, v78 row_shr:2 row_mask:0xf bank_mask:0xf bound_ctrl:0
	v_fmac_f32_dpp v251, v43, v79 row_shr:2 row_mask:0xf bank_mask:0xf bound_ctrl:0
	v_fmac_f32_dpp v244, v92, v56 row_shl:14 row_mask:0xf bank_mask:0xf bound_ctrl:0
	v_fmac_f32_dpp v245, v93, v57 row_shl:14 row_mask:0xf bank_mask:0xf bound_ctrl:0
	v_fmac_f32_dpp v246, v94, v58 row_shl:14 row_mask:0xf bank_mask:0xf bound_ctrl:0
	v_fmac_f32_dpp v247, v95, v59 row_shl:14 row_mask:0xf bank_mask:0xf bound_ctrl:0
	v_fmac_f32_dpp v248, v88, v76 row_shl:14 row_mask:0xf bank_mask:0xf bound_ctrl:0
	v_fmac_f32_dpp v249, v89, v77 row_shl:14 row_mask:0xf bank_mask:0xf bound_ctrl:0
	v_fmac_f32_dpp v250, v90, v78 row_shl:14 row_mask:0xf bank_mask:0xf bound_ctrl:0
	v_fmac_f32_dpp v251, v91, v79 row_shl:14 row_mask:0xf bank_mask:0xf bound_ctrl:0
	v_fmac_f32_dpp v244, v44, v60 row_shr:1 row_mask:0xf bank_mask:0xf bound_ctrl:0
	v_fmac_f32_dpp v245, v45, v61 row_shr:1 row_mask:0xf bank_mask:0xf bound_ctrl:0
	v_fmac_f32_dpp v246, v46, v62 row_shr:1 row_mask:0xf bank_mask:0xf bound_ctrl:0
	v_fmac_f32_dpp v247, v47, v63 row_shr:1 row_mask:0xf bank_mask:0xf bound_ctrl:0
	v_fmac_f32_dpp v248, v40, v80 row_shr:1 row_mask:0xf bank_mask:0xf bound_ctrl:0
	v_fmac_f32_dpp v249, v41, v81 row_shr:1 row_mask:0xf bank_mask:0xf bound_ctrl:0
	v_fmac_f32_dpp v250, v42, v82 row_shr:1 row_mask:0xf bank_mask:0xf bound_ctrl:0
	v_fmac_f32_dpp v251, v43, v83 row_shr:1 row_mask:0xf bank_mask:0xf bound_ctrl:0
	v_fmac_f32_dpp v244, v92, v60 row_shl:15 row_mask:0xf bank_mask:0xf bound_ctrl:0
	v_fmac_f32_dpp v245, v93, v61 row_shl:15 row_mask:0xf bank_mask:0xf bound_ctrl:0
	v_fmac_f32_dpp v246, v94, v62 row_shl:15 row_mask:0xf bank_mask:0xf bound_ctrl:0
	v_fmac_f32_dpp v247, v95, v63 row_shl:15 row_mask:0xf bank_mask:0xf bound_ctrl:0
	v_fmac_f32_dpp v248, v88, v80 row_shl:15 row_mask:0xf bank_mask:0xf bound_ctrl:0
	v_fmac_f32_dpp v249, v89, v81 row_shl:15 row_mask:0xf bank_mask:0xf bound_ctrl:0
	v_fmac_f32_dpp v250, v90, v82 row_shl:15 row_mask:0xf bank_mask:0xf bound_ctrl:0
	v_fmac_f32_dpp v251, v91, v83 row_shl:15 row_mask:0xf bank_mask:0xf bound_ctrl:0
	v_fmac_f32_e32 v244, v64, v44
	v_fmac_f32_e32 v245, v65, v45
	v_fmac_f32_e32 v246, v66, v46
	v_fmac_f32_e32 v247, v67, v47
	v_fmac_f32_e32 v248, v84, v40
	v_fmac_f32_e32 v249, v85, v41
	v_fmac_f32_e32 v250, v86, v42
	v_fmac_f32_e32 v251, v87, v43
	v_pk_mul_f32 v[210:211], v[244:245], s[100:101]
	v_pk_mul_f32 v[212:213], v[246:247], s[100:101]
	v_pk_mul_f32 v[216:217], v[248:249], s[100:101]
	v_pk_mul_f32 v[220:221], v[250:251], s[100:101]
	v_exp_f32_e32 v210, v210
	v_exp_f32_e32 v211, v211
	v_exp_f32_e32 v212, v212
	v_exp_f32_e32 v213, v213
	v_exp_f32_e32 v216, v216
	v_exp_f32_e32 v217, v217
	v_exp_f32_e32 v220, v220
	v_exp_f32_e32 v221, v221
	v_pk_add_f32 v[210:211], v[210:211], 1.0 op_sel_hi:[1,0]
	v_pk_add_f32 v[212:213], v[212:213], 1.0 op_sel_hi:[1,0]
	v_pk_add_f32 v[216:217], v[216:217], 1.0 op_sel_hi:[1,0]
	v_pk_add_f32 v[220:221], v[220:221], 1.0 op_sel_hi:[1,0]
	v_rcp_f32_e32 v210, v210
	v_rcp_f32_e32 v211, v211
	v_rcp_f32_e32 v212, v212
	v_rcp_f32_e32 v213, v213
	v_rcp_f32_e32 v216, v216
	v_rcp_f32_e32 v217, v217
	v_rcp_f32_e32 v220, v220
	v_rcp_f32_e32 v221, v221
	v_pk_mul_f32 v[244:245], v[244:245], v[210:211]
	v_pk_mul_f32 v[246:247], v[246:247], v[212:213]
	v_pk_mul_f32 v[248:249], v[248:249], v[216:217]
	v_pk_mul_f32 v[250:251], v[250:251], v[220:221]
	v_pk_mul_f32 v[244:245], v[32:33], v[244:245]
	v_pk_mul_f32 v[246:247], v[34:35], v[246:247]
	v_pk_mul_f32 v[248:249], v[36:37], v[248:249]
	v_pk_mul_f32 v[250:251], v[38:39], v[250:251]
	v_cvt_pk_bf16_f32 v240, v244, v245
	v_cvt_pk_bf16_f32 v241, v246, v247
	v_cvt_pk_bf16_f32 v242, v248, v249
	v_cvt_pk_bf16_f32 v243, v250, v251
	v_lshl_add_u64 v[234:235], v[234:235], 0, v[238:239]
	s_and_b64 s[12:13], s[12:13], s[14:15]
	s_and_saveexec_b64 s[62:63], s[12:13]
	global_store_dwordx4 v[234:235], v[240:243], off
	s_or_b64 exec, exec, s[62:63]
	s_cmp_eq_u64 vcc, 0
	s_cbranch_scc1 .Lgu_nrl5
	global_load_dwordx4 v[76:79], v229, s[50:51] offset:16
	global_load_dwordx4 v[56:59], v229, s[50:51]
	global_load_dwordx4 v[80:83], v229, s[46:47] offset:16
	global_load_dwordx4 v[60:63], v229, s[46:47]
	s_waitcnt vmcnt(0)
.Lgu_nrl5:
	v_fmamk_f32 v230, v197, 0x39800000, v191
	v_rsq_f32_e32 v230, v230
	v_and_b32_e32 v224, 0xfff, v194
	v_cmp_le_i32_e64 s[12:13], s53, v194
	v_cmp_gt_i32_e64 s[14:15], s88, v181
	v_cmp_gt_u32_e32 vcc, 2, v224
	v_pk_mul_f32 v[28:29], v[28:29], v[230:231] op_sel_hi:[1,0]
	v_pk_mul_f32 v[30:31], v[30:31], v[230:231] op_sel_hi:[1,0]
	v_pk_mul_f32 v[24:25], v[24:25], v[230:231] op_sel_hi:[1,0]
	v_pk_mul_f32 v[26:27], v[26:27], v[230:231] op_sel_hi:[1,0]
	v_pk_mul_f32 v[16:17], v[16:17], v[230:231] op_sel_hi:[1,0]
	v_pk_mul_f32 v[18:19], v[18:19], v[230:231] op_sel_hi:[1,0]
	v_pk_mul_f32 v[20:21], v[20:21], v[230:231] op_sel_hi:[1,0]
	v_pk_mul_f32 v[22:23], v[22:23], v[230:231] op_sel_hi:[1,0]
	s_cmp_eq_u64 vcc, 0
	s_cbranch_scc1 .Lgu_nss6
	v_cmp_eq_u32_e64 s[98:99], 0, v224
	s_nop 1
	v_cndmask_b32_e64 v56, v56, 0, vcc
	v_cndmask_b32_e64 v57, v57, 0, vcc
	v_cndmask_b32_e64 v58, v58, 0, vcc
	v_cndmask_b32_e64 v59, v59, 0, vcc
	v_cndmask_b32_e64 v76, v76, 0, vcc
	v_cndmask_b32_e64 v77, v77, 0, vcc
	v_cndmask_b32_e64 v78, v78, 0, vcc
	v_cndmask_b32_e64 v79, v79, 0, vcc
	v_cndmask_b32_e64 v60, v60, 0, s[98:99]
	v_cndmask_b32_e64 v61, v61, 0, s[98:99]
	v_cndmask_b32_e64 v62, v62, 0, s[98:99]
	v_cndmask_b32_e64 v63, v63, 0, s[98:99]
	v_cndmask_b32_e64 v80, v80, 0, s[98:99]
	v_cndmask_b32_e64 v81, v81, 0, s[98:99]
	v_cndmask_b32_e64 v82, v82, 0, s[98:99]
	v_cndmask_b32_e64 v83, v83, 0, s[98:99]
.Lgu_nss6:
	v_mov_b32_e32 v244, v52
	v_mov_b32_e32 v245, v53
	v_mov_b32_e32 v246, v54
	v_mov_b32_e32 v247, v55
	v_mov_b32_e32 v248, v72
	v_mov_b32_e32 v249, v73
	v_mov_b32_e32 v250, v74
	v_mov_b32_e32 v251, v75
	v_fmac_f32_dpp v244, v28, v56 row_shr:2 row_mask:0xf bank_mask:0xf bound_ctrl:0
	v_fmac_f32_dpp v245, v29, v57 row_shr:2 row_mask:0xf bank_mask:0xf bound_ctrl:0
	v_fmac_f32_dpp v246, v30, v58 row_shr:2 row_mask:0xf bank_mask:0xf bound_ctrl:0
	v_fmac_f32_dpp v247, v31, v59 row_shr:2 row_mask:0xf bank_mask:0xf bound_ctrl:0
	v_fmac_f32_dpp v248, v24, v76 row_shr:2 row_mask:0xf bank_mask:0xf bound_ctrl:0
	v_fmac_f32_dpp v249, v25, v77 row_shr:2 row_mask:0xf bank_mask:0xf bound_ctrl:0
	v_fmac_f32_dpp v250, v26, v78 row_shr:2 row_mask:0xf bank_mask:0xf bound_ctrl:0
	v_fmac_f32_dpp v251, v27, v79 row_shr:2 row_mask:0xf bank_mask:0xf bound_ctrl:0
	v_fmac_f32_dpp v244, v44, v56 row_shl:14 row_mask:0xf bank_mask:0xf bound_ctrl:0
	v_fmac_f32_dpp v245, v45, v57 row_shl:14 row_mask:0xf bank_mask:0xf bound_ctrl:0
	v_fmac_f32_dpp v246, v46, v58 row_shl:14 row_mask:0xf bank_mask:0xf bound_ctrl:0
	v_fmac_f32_dpp v247, v47, v59 row_shl:14 row_mask:0xf bank_mask:0xf bound_ctrl:0
	v_fmac_f32_dpp v248, v40, v76 row_shl:14 row_mask:0xf bank_mask:0xf bound_ctrl:0
	v_fmac_f32_dpp v249, v41, v77 row_shl:14 row_mask:0xf bank_mask:0xf bound_ctrl:0
	v_fmac_f32_dpp v250, v42, v78 row_shl:14 row_mask:0xf bank_mask:0xf bound_ctrl:0
	v_fmac_f32_dpp v251, v43, v79 row_shl:14 row_mask:0xf bank_mask:0xf bound_ctrl:0
	v_fmac_f32_dpp v244, v28, v60 row_shr:1 row_mask:0xf bank_mask:0xf bound_ctrl:0
	v_fmac_f32_dpp v245, v29, v61 row_shr:1 row_mask:0xf bank_mask:0xf bound_ctrl:0
	v_fmac_f32_dpp v246, v30, v62 row_shr:1 row_mask:0xf bank_mask:0xf bound_ctrl:0
	v_fmac_f32_dpp v247, v31, v63 row_shr:1 row_mask:0xf bank_mask:0xf bound_ctrl:0
	v_fmac_f32_dpp v248, v24, v80 row_shr:1 row_mask:0xf bank_mask:0xf bound_ctrl:0
	v_fmac_f32_dpp v249, v25, v81 row_shr:1 row_mask:0xf bank_mask:0xf bound_ctrl:0
	v_fmac_f32_dpp v250, v26, v82 row_shr:1 row_mask:0xf bank_mask:0xf bound_ctrl:0
	v_fmac_f32_dpp v251, v27, v83 row_shr:1 row_mask:0xf bank_mask:0xf bound_ctrl:0
	v_fmac_f32_dpp v244, v44, v60 row_shl:15 row_mask:0xf bank_mask:0xf bound_ctrl:0
	v_fmac_f32_dpp v245, v45, v61 row_shl:15 row_mask:0xf bank_mask:0xf bound_ctrl:0
	v_fmac_f32_dpp v246, v46, v62 row_shl:15 row_mask:0xf bank_mask:0xf bound_ctrl:0
	v_fmac_f32_dpp v247, v47, v63 row_shl:15 row_mask:0xf bank_mask:0xf bound_ctrl:0
	v_fmac_f32_dpp v248, v40, v80 row_shl:15 row_mask:0xf bank_mask:0xf bound_ctrl:0
	v_fmac_f32_dpp v249, v41, v81 row_shl:15 row_mask:0xf bank_mask:0xf bound_ctrl:0
	v_fmac_f32_dpp v250, v42, v82 row_shl:15 row_mask:0xf bank_mask:0xf bound_ctrl:0
	v_fmac_f32_dpp v251, v43, v83 row_shl:15 row_mask:0xf bank_mask:0xf bound_ctrl:0
	v_fmac_f32_e32 v244, v64, v28
	v_fmac_f32_e32 v245, v65, v29
	v_fmac_f32_e32 v246, v66, v30
	v_fmac_f32_e32 v247, v67, v31
	v_fmac_f32_e32 v248, v84, v24
	v_fmac_f32_e32 v249, v85, v25
	v_fmac_f32_e32 v250, v86, v26
	v_fmac_f32_e32 v251, v87, v27
	v_pk_mul_f32 v[210:211], v[244:245], s[100:101]
	v_pk_mul_f32 v[212:213], v[246:247], s[100:101]
	v_pk_mul_f32 v[216:217], v[248:249], s[100:101]
	v_pk_mul_f32 v[220:221], v[250:251], s[100:101]
	v_exp_f32_e32 v210, v210
	v_exp_f32_e32 v211, v211
	v_exp_f32_e32 v212, v212
	v_exp_f32_e32 v213, v213
	v_exp_f32_e32 v216, v216
	v_exp_f32_e32 v217, v217
	v_exp_f32_e32 v220, v220
	v_exp_f32_e32 v221, v221
	v_pk_add_f32 v[210:211], v[210:211], 1.0 op_sel_hi:[1,0]
	v_pk_add_f32 v[212:213], v[212:213], 1.0 op_sel_hi:[1,0]
	v_pk_add_f32 v[216:217], v[216:217], 1.0 op_sel_hi:[1,0]
	v_pk_add_f32 v[220:221], v[220:221], 1.0 op_sel_hi:[1,0]
	v_rcp_f32_e32 v210, v210
	v_rcp_f32_e32 v211, v211
	v_rcp_f32_e32 v212, v212
	v_rcp_f32_e32 v213, v213
	v_rcp_f32_e32 v216, v216
	v_rcp_f32_e32 v217, v217
	v_rcp_f32_e32 v220, v220
	v_rcp_f32_e32 v221, v221
	v_pk_mul_f32 v[244:245], v[244:245], v[210:211]
	v_pk_mul_f32 v[246:247], v[246:247], v[212:213]
	v_pk_mul_f32 v[248:249], v[248:249], v[216:217]
	v_pk_mul_f32 v[250:251], v[250:251], v[220:221]
	v_pk_mul_f32 v[244:245], v[16:17], v[244:245]
	v_pk_mul_f32 v[246:247], v[18:19], v[246:247]
	v_pk_mul_f32 v[248:249], v[20:21], v[248:249]
	v_pk_mul_f32 v[250:251], v[22:23], v[250:251]
	v_cvt_pk_bf16_f32 v240, v244, v245
	v_cvt_pk_bf16_f32 v241, v246, v247
	v_cvt_pk_bf16_f32 v242, v248, v249
	v_cvt_pk_bf16_f32 v243, v250, v251
	v_lshl_add_u64 v[234:235], v[234:235], 0, v[238:239]
	s_and_b64 s[12:13], s[12:13], s[14:15]
	s_and_saveexec_b64 s[62:63], s[12:13]
	global_store_dwordx4 v[234:235], v[240:243], off
	s_or_b64 exec, exec, s[62:63]
	s_cmp_eq_u64 vcc, 0
	s_cbranch_scc1 .Lgu_nrl6
	global_load_dwordx4 v[76:79], v229, s[50:51] offset:16
	global_load_dwordx4 v[56:59], v229, s[50:51]
	global_load_dwordx4 v[80:83], v229, s[46:47] offset:16
	global_load_dwordx4 v[60:63], v229, s[46:47]
	s_waitcnt vmcnt(0)
.Lgu_nrl6:
	v_and_b32_e32 v224, 0xfff, v193
	v_cmp_le_i32_e64 s[12:13], s53, v193
	v_cmp_gt_i32_e64 s[14:15], s89, v181
	v_cmp_gt_u32_e32 vcc, 2, v224
	v_pk_mul_f32 v[12:13], v[12:13], v[180:181] op_sel_hi:[1,0]
	v_pk_mul_f32 v[14:15], v[14:15], v[180:181] op_sel_hi:[1,0]
	v_pk_mul_f32 v[8:9], v[8:9], v[180:181] op_sel_hi:[1,0]
	v_pk_mul_f32 v[10:11], v[10:11], v[180:181] op_sel_hi:[1,0]
	v_pk_mul_f32 v[0:1], v[0:1], v[180:181] op_sel_hi:[1,0]
	v_pk_mul_f32 v[2:3], v[2:3], v[180:181] op_sel_hi:[1,0]
	v_pk_mul_f32 v[4:5], v[4:5], v[180:181] op_sel_hi:[1,0]
	v_pk_mul_f32 v[6:7], v[6:7], v[180:181] op_sel_hi:[1,0]
	s_cmp_eq_u64 vcc, 0
	s_cbranch_scc1 .Lgu_nss7
	v_cmp_eq_u32_e64 s[98:99], 0, v224
	s_nop 1
	v_cndmask_b32_e64 v56, v56, 0, vcc
	v_cndmask_b32_e64 v57, v57, 0, vcc
	v_cndmask_b32_e64 v58, v58, 0, vcc
	v_cndmask_b32_e64 v59, v59, 0, vcc
	v_cndmask_b32_e64 v76, v76, 0, vcc
	v_cndmask_b32_e64 v77, v77, 0, vcc
	v_cndmask_b32_e64 v78, v78, 0, vcc
	v_cndmask_b32_e64 v79, v79, 0, vcc
	v_cndmask_b32_e64 v60, v60, 0, s[98:99]
	v_cndmask_b32_e64 v61, v61, 0, s[98:99]
	v_cndmask_b32_e64 v62, v62, 0, s[98:99]
	v_cndmask_b32_e64 v63, v63, 0, s[98:99]
	v_cndmask_b32_e64 v80, v80, 0, s[98:99]
	v_cndmask_b32_e64 v81, v81, 0, s[98:99]
	v_cndmask_b32_e64 v82, v82, 0, s[98:99]
	v_cndmask_b32_e64 v83, v83, 0, s[98:99]
.Lgu_nss7:
	v_mov_b32_e32 v244, v52
	v_mov_b32_e32 v245, v53
	v_mov_b32_e32 v246, v54
	v_mov_b32_e32 v247, v55
	v_mov_b32_e32 v248, v72
	v_mov_b32_e32 v249, v73
	v_mov_b32_e32 v250, v74
	v_mov_b32_e32 v251, v75
	v_fmac_f32_dpp v244, v12, v56 row_shr:2 row_mask:0xf bank_mask:0xf bound_ctrl:0
	v_fmac_f32_dpp v245, v13, v57 row_shr:2 row_mask:0xf bank_mask:0xf bound_ctrl:0
	v_fmac_f32_dpp v246, v14, v58 row_shr:2 row_mask:0xf bank_mask:0xf bound_ctrl:0
	v_fmac_f32_dpp v247, v15, v59 row_shr:2 row_mask:0xf bank_mask:0xf bound_ctrl:0
	v_fmac_f32_dpp v248, v8, v76 row_shr:2 row_mask:0xf bank_mask:0xf bound_ctrl:0
	v_fmac_f32_dpp v249, v9, v77 row_shr:2 row_mask:0xf bank_mask:0xf bound_ctrl:0
	v_fmac_f32_dpp v250, v10, v78 row_shr:2 row_mask:0xf bank_mask:0xf bound_ctrl:0
	v_fmac_f32_dpp v251, v11, v79 row_shr:2 row_mask:0xf bank_mask:0xf bound_ctrl:0
	v_fmac_f32_dpp v244, v28, v56 row_shl:14 row_mask:0xf bank_mask:0xf bound_ctrl:0
	v_fmac_f32_dpp v245, v29, v57 row_shl:14 row_mask:0xf bank_mask:0xf bound_ctrl:0
	v_fmac_f32_dpp v246, v30, v58 row_shl:14 row_mask:0xf bank_mask:0xf bound_ctrl:0
	v_fmac_f32_dpp v247, v31, v59 row_shl:14 row_mask:0xf bank_mask:0xf bound_ctrl:0
	v_fmac_f32_dpp v248, v24, v76 row_shl:14 row_mask:0xf bank_mask:0xf bound_ctrl:0
	v_fmac_f32_dpp v249, v25, v77 row_shl:14 row_mask:0xf bank_mask:0xf bound_ctrl:0
	v_fmac_f32_dpp v250, v26, v78 row_shl:14 row_mask:0xf bank_mask:0xf bound_ctrl:0
	v_fmac_f32_dpp v251, v27, v79 row_shl:14 row_mask:0xf bank_mask:0xf bound_ctrl:0
	v_fmac_f32_dpp v244, v12, v60 row_shr:1 row_mask:0xf bank_mask:0xf bound_ctrl:0
	v_fmac_f32_dpp v245, v13, v61 row_shr:1 row_mask:0xf bank_mask:0xf bound_ctrl:0
	v_fmac_f32_dpp v246, v14, v62 row_shr:1 row_mask:0xf bank_mask:0xf bound_ctrl:0
	v_fmac_f32_dpp v247, v15, v63 row_shr:1 row_mask:0xf bank_mask:0xf bound_ctrl:0
	v_fmac_f32_dpp v248, v8, v80 row_shr:1 row_mask:0xf bank_mask:0xf bound_ctrl:0
	v_fmac_f32_dpp v249, v9, v81 row_shr:1 row_mask:0xf bank_mask:0xf bound_ctrl:0
	v_fmac_f32_dpp v250, v10, v82 row_shr:1 row_mask:0xf bank_mask:0xf bound_ctrl:0
	v_fmac_f32_dpp v251, v11, v83 row_shr:1 row_mask:0xf bank_mask:0xf bound_ctrl:0
	v_fmac_f32_dpp v244, v28, v60 row_shl:15 row_mask:0xf bank_mask:0xf bound_ctrl:0
	v_fmac_f32_dpp v245, v29, v61 row_shl:15 row_mask:0xf bank_mask:0xf bound_ctrl:0
	v_fmac_f32_dpp v246, v30, v62 row_shl:15 row_mask:0xf bank_mask:0xf bound_ctrl:0
	v_fmac_f32_dpp v247, v31, v63 row_shl:15 row_mask:0xf bank_mask:0xf bound_ctrl:0
	v_fmac_f32_dpp v248, v24, v80 row_shl:15 row_mask:0xf bank_mask:0xf bound_ctrl:0
	v_fmac_f32_dpp v249, v25, v81 row_shl:15 row_mask:0xf bank_mask:0xf bound_ctrl:0
	v_fmac_f32_dpp v250, v26, v82 row_shl:15 row_mask:0xf bank_mask:0xf bound_ctrl:0
	v_fmac_f32_dpp v251, v27, v83 row_shl:15 row_mask:0xf bank_mask:0xf bound_ctrl:0
	v_fmac_f32_e32 v244, v64, v12
	v_fmac_f32_e32 v245, v65, v13
	v_fmac_f32_e32 v246, v66, v14
	v_fmac_f32_e32 v247, v67, v15
	v_fmac_f32_e32 v248, v84, v8
	v_fmac_f32_e32 v249, v85, v9
	v_fmac_f32_e32 v250, v86, v10
	v_fmac_f32_e32 v251, v87, v11
	v_pk_mul_f32 v[210:211], v[244:245], s[100:101]
	v_pk_mul_f32 v[212:213], v[246:247], s[100:101]
	v_pk_mul_f32 v[216:217], v[248:249], s[100:101]
	v_pk_mul_f32 v[220:221], v[250:251], s[100:101]
	v_exp_f32_e32 v210, v210
	v_exp_f32_e32 v211, v211
	v_exp_f32_e32 v212, v212
	v_exp_f32_e32 v213, v213
	v_exp_f32_e32 v216, v216
	v_exp_f32_e32 v217, v217
	v_exp_f32_e32 v220, v220
	v_exp_f32_e32 v221, v221
	v_pk_add_f32 v[210:211], v[210:211], 1.0 op_sel_hi:[1,0]
	v_pk_add_f32 v[212:213], v[212:213], 1.0 op_sel_hi:[1,0]
	v_pk_add_f32 v[216:217], v[216:217], 1.0 op_sel_hi:[1,0]
	v_pk_add_f32 v[220:221], v[220:221], 1.0 op_sel_hi:[1,0]
	v_rcp_f32_e32 v210, v210
	v_rcp_f32_e32 v211, v211
	v_rcp_f32_e32 v212, v212
	v_rcp_f32_e32 v213, v213
	v_rcp_f32_e32 v216, v216
	v_rcp_f32_e32 v217, v217
	v_rcp_f32_e32 v220, v220
	v_rcp_f32_e32 v221, v221
	v_pk_mul_f32 v[244:245], v[244:245], v[210:211]
	v_pk_mul_f32 v[246:247], v[246:247], v[212:213]
	v_pk_mul_f32 v[248:249], v[248:249], v[216:217]
	v_pk_mul_f32 v[250:251], v[250:251], v[220:221]
	v_pk_mul_f32 v[244:245], v[0:1], v[244:245]
	v_pk_mul_f32 v[246:247], v[2:3], v[246:247]
	v_pk_mul_f32 v[248:249], v[4:5], v[248:249]
	v_pk_mul_f32 v[250:251], v[6:7], v[250:251]
	v_cvt_pk_bf16_f32 v240, v244, v245
	v_cvt_pk_bf16_f32 v241, v246, v247
	v_cvt_pk_bf16_f32 v242, v248, v249
	v_cvt_pk_bf16_f32 v243, v250, v251
	v_lshl_add_u64 v[234:235], v[234:235], 0, v[238:239]
	s_and_b64 s[12:13], s[12:13], s[14:15]
	s_and_saveexec_b64 s[62:63], s[12:13]
	global_store_dwordx4 v[234:235], v[240:243], off
	s_or_b64 exec, exec, s[62:63]
	s_cmp_eq_u64 vcc, 0
	s_cbranch_scc1 .Lgu_nrl7
	global_load_dwordx4 v[76:79], v229, s[50:51] offset:16
	global_load_dwordx4 v[56:59], v229, s[50:51]
	global_load_dwordx4 v[80:83], v229, s[46:47] offset:16
	global_load_dwordx4 v[60:63], v229, s[46:47]
	s_waitcnt vmcnt(0)
.Lgu_nrl7:
	s_branch .LBB0_677
